# v013 + residual-GEMM epilogue: both 128-row halves of the X read-modify-write loaded up front (second half into free fragment registers)
# speedup vs baseline: 1.0070x; 1.0023x over previous
; DI u32x4 pack8(f32x4 a, f32x4 b) { u32x4 w; w.x = pk2(a[0], a[1]); w.y = pk2(a[2], a[3]); w.z = pk2(b[0], b[1]); w.w = pk2(b[2], b[3]); return w; }
;     DI void operator()(const pg8::Acc& acc, const pg8::Unit& u, int wr, int wc, int fr, int fq) const {
;         const int row0 = u.pm * 256 + wr * 64 + fr, col0 = u.pn * 256 + wc * 32 + 8 * fq;
;         if (u.kind == 0) {
;             float* X = (float*)(ws + WS_X); float* SSP = (float*)(ws + WS_SSP) + (size_t)site * MT * 16;
; #pragma unroll
;             for (int ai = 0; ai < 2; ++ai) {
;                 bf16* XH = (bf16*)X;
;                 u32x4 xv[4][2];
; #pragma unroll
;                 for (int m = 0; m < 4; ++m)
; #pragma unroll
;                     for (int bj = 0; bj < 2; ++bj) xv[m][bj] = *(const u32x4*)(XH + (size_t)(row0 + ai * 128 + m * 16) * DM + col0 + bj * 128);
; #pragma unroll
;                 for (int m = 0; m < 4; ++m) { const int row = row0 + ai * 128 + m * 16; float ssq = 0.f;
; #pragma unroll
;                     for (int bj = 0; bj < 2; ++bj) { const u32x4 x = xv[m][bj];
;                         const f32x4 xa = (f32x4){bflo(x.x), bfhi(x.x), bflo(x.y), bfhi(x.y)} + acc[ai][bj][m][0] * scale, xb = (f32x4){bflo(x.z), bfhi(x.z), bflo(x.w), bfhi(x.w)} + acc[ai][bj][m][1] * scale;
;                         *(u32x4*)(XH + (size_t)row * DM + col0 + bj * 128) = pack8(xa, xb);
;                         ssq += ((xa[0] * xa[0] + xa[1] * xa[1]) + (xa[2] * xa[2] + xa[3] * xa[3])) + ((xb[0] * xb[0] + xb[1] * xb[1]) + (xb[2] * xb[2] + xb[3] * xb[3])); }
;                     ssq += __shfl_xor(ssq, 16); ssq += __shfl_xor(ssq, 32);
;                     if (fq == 0) SSP[(size_t)row * 16 + u.pn * 4 + wc] = ssq; }
;             }
.LBB0_417:
	v_lshl_add_u64 v[176:177], v[132:133], 1, s[8:9]
	v_and_b32_e32 v133, 64, v198
	v_xor_b32_e32 v132, 16, v198
	v_add_u32_e32 v133, 64, v133
	v_cmp_lt_i32_e32 vcc, v132, v133
	v_or_b32_e32 v186, 16, v174
	v_ashrrev_i32_e32 v187, 31, v186
	v_cndmask_b32_e32 v132, v198, v132, vcc
	v_lshlrev_b32_e32 v195, 2, v132
	v_xor_b32_e32 v132, 32, v198
	v_cmp_lt_i32_e32 vcc, v132, v133
	v_or_b32_e32 v182, 32, v174
	v_ashrrev_i32_e32 v183, 31, v182
	v_cndmask_b32_e32 v132, v198, v132, vcc
	v_lshlrev_b32_e32 v194, 2, v132
	v_lshlrev_b64 v[132:133], 11, v[174:175]
	v_lshl_add_u64 v[190:191], v[176:177], 0, v[132:133]
	global_load_dwordx4 v[202:205], v[190:191], off
	global_load_dwordx4 v[156:159], v[190:191], off offset:256
	v_lshlrev_b64 v[132:133], 11, v[186:187]
	v_or_b32_e32 v178, 48, v174
	v_lshl_add_u64 v[188:189], v[176:177], 0, v[132:133]
	v_lshlrev_b64 v[132:133], 11, v[182:183]
	v_ashrrev_i32_e32 v179, 31, v178
	v_lshl_add_u64 v[184:185], v[176:177], 0, v[132:133]
	v_lshlrev_b64 v[132:133], 11, v[178:179]
	v_lshl_add_u64 v[180:181], v[176:177], 0, v[132:133]
	global_load_dwordx4 v[152:155], v[188:189], off
	global_load_dwordx4 v[148:151], v[188:189], off offset:256
	global_load_dwordx4 v[144:147], v[184:185], off
	global_load_dwordx4 v[140:143], v[184:185], off offset:256
	global_load_dwordx4 v[136:139], v[180:181], off
	global_load_dwordx4 v[132:135], v[180:181], off offset:256
	v_lshl_add_u64 v[240:241], s[88:89], 1, v[190:191]
	v_lshl_add_u64 v[242:243], s[88:89], 1, v[188:189]
	v_lshl_add_u64 v[244:245], s[88:89], 1, v[184:185]
	v_lshl_add_u64 v[246:247], s[88:89], 1, v[180:181]
	global_load_dwordx4 v[208:211], v[240:241], off
	global_load_dwordx4 v[212:215], v[240:241], off offset:256
	global_load_dwordx4 v[216:219], v[242:243], off
	global_load_dwordx4 v[220:223], v[242:243], off offset:256
	global_load_dwordx4 v[224:227], v[244:245], off
	global_load_dwordx4 v[228:231], v[244:245], off offset:256
	global_load_dwordx4 v[232:235], v[246:247], off
	global_load_dwordx4 v[236:239], v[246:247], off offset:256
	s_waitcnt vmcnt(0)
	v_lshlrev_b32_e32 v206, 16, v202
	v_and_b32_e32 v207, 0xffff0000, v202
	v_lshlrev_b32_e32 v202, 16, v203
	v_and_b32_e32 v203, 0xffff0000, v203
	v_pk_fma_f32 v[130:131], v[130:131], 0.5, v[202:203] op_sel_hi:[1,0,1]
	v_lshlrev_b32_e32 v202, 16, v204
	v_and_b32_e32 v203, 0xffff0000, v204
	v_lshlrev_b32_e32 v204, 16, v205
	v_and_b32_e32 v205, 0xffff0000, v205
	v_pk_fma_f32 v[128:129], v[128:129], 0.5, v[206:207] op_sel_hi:[1,0,1]
	v_pk_fma_f32 v[204:205], v[126:127], 0.5, v[204:205] op_sel_hi:[1,0,1]
	v_pk_fma_f32 v[202:203], v[124:125], 0.5, v[202:203] op_sel_hi:[1,0,1]
	v_cvt_pk_bf16_f32 v124, v128, v129
	v_cvt_pk_bf16_f32 v125, v130, v131
	v_cvt_pk_bf16_f32 v126, v202, v203
	v_cvt_pk_bf16_f32 v127, v204, v205
	global_store_dwordx4 v[190:191], v[124:127], off
	s_nop 1
	v_mul_f32_e32 v124, v129, v129
	v_mul_f32_e32 v125, v131, v131
	v_fmac_f32_e32 v124, v128, v128
	v_fmac_f32_e32 v125, v130, v130
	v_add_f32_e32 v124, v124, v125
	v_mul_f32_e32 v125, v203, v203
	v_mul_f32_e32 v126, v205, v205
	v_fmac_f32_e32 v125, v202, v202
	v_fmac_f32_e32 v126, v204, v204
	v_add_f32_e32 v125, v125, v126
	v_add_f32_e32 v128, v124, v125
	v_lshlrev_b32_e32 v124, 16, v156
	v_and_b32_e32 v125, 0xffff0000, v156
	v_lshlrev_b32_e32 v126, 16, v157
	v_and_b32_e32 v127, 0xffff0000, v157
	v_pk_fma_f32 v[122:123], v[122:123], 0.5, v[126:127] op_sel_hi:[1,0,1]
	v_pk_fma_f32 v[120:121], v[120:121], 0.5, v[124:125] op_sel_hi:[1,0,1]
	v_lshlrev_b32_e32 v124, 16, v158
	v_and_b32_e32 v125, 0xffff0000, v158
	v_lshlrev_b32_e32 v126, 16, v159
	v_and_b32_e32 v127, 0xffff0000, v159
	v_pk_fma_f32 v[126:127], v[118:119], 0.5, v[126:127] op_sel_hi:[1,0,1]
	v_pk_fma_f32 v[124:125], v[116:117], 0.5, v[124:125] op_sel_hi:[1,0,1]
	v_cvt_pk_bf16_f32 v116, v120, v121
	v_cvt_pk_bf16_f32 v117, v122, v123
	v_cvt_pk_bf16_f32 v118, v124, v125
	v_cvt_pk_bf16_f32 v119, v126, v127
	global_store_dwordx4 v[190:191], v[116:119], off offset:256
	s_nop 1
	v_mul_f32_e32 v116, v121, v121
	v_mul_f32_e32 v117, v123, v123
	v_fmac_f32_e32 v116, v120, v120
	v_fmac_f32_e32 v117, v122, v122
	v_add_f32_e32 v116, v116, v117
	v_mul_f32_e32 v117, v125, v125
	v_mul_f32_e32 v118, v127, v127
	v_fmac_f32_e32 v117, v124, v124
	v_fmac_f32_e32 v118, v126, v126
	v_add_f32_e32 v117, v117, v118
	v_add_f32_e32 v116, v116, v117
	v_add_f32_e32 v116, v128, v116
	ds_bpermute_b32 v117, v195, v116
	s_waitcnt lgkmcnt(0)
	v_add_f32_e32 v116, v116, v117
	ds_bpermute_b32 v117, v194, v116
	s_and_saveexec_b64 s[18:19], s[2:3]
	s_cbranch_execz .LBB0_419
	s_waitcnt lgkmcnt(0)
	v_add_f32_e32 v118, v116, v117
	s_lshl_b32 s20, s37, 2
	v_lshlrev_b64 v[116:117], 6, v[174:175]
	s_ashr_i32 s21, s20, 31
	v_lshl_add_u64 v[116:117], s[10:11], 0, v[116:117]
	v_lshl_add_u64 v[116:117], s[20:21], 2, v[116:117]
	s_lshl_b32 s62, s43, 2
	v_lshl_add_u64 v[116:117], v[116:117], 0, s[62:63]
	global_store_dword v[116:117], v118, off

; DI u32x4 pack8(f32x4 a, f32x4 b) { u32x4 w; w.x = pk2(a[0], a[1]); w.y = pk2(a[2], a[3]); w.z = pk2(b[0], b[1]); w.w = pk2(b[2], b[3]); return w; }
;     DI void operator()(const pg8::Acc& acc, const pg8::Unit& u, int wr, int wc, int fr, int fq) const {
;     ...
;             float* X = (float*)(ws + WS_X); float* SSP = (float*)(ws + WS_SSP) + (size_t)site * MT * 16;
; #pragma unroll
;             for (int ai = 0; ai < 2; ++ai) {
;                 bf16* XH = (bf16*)X;
;                 u32x4 xv[4][2];
; #pragma unroll
;                 for (int m = 0; m < 4; ++m)
; #pragma unroll
;                     for (int bj = 0; bj < 2; ++bj) xv[m][bj] = *(const u32x4*)(XH + (size_t)(row0 + ai * 128 + m * 16) * DM + col0 + bj * 128);
; #pragma unroll
;                 for (int m = 0; m < 4; ++m) { const int row = row0 + ai * 128 + m * 16; float ssq = 0.f;
; #pragma unroll
;                     for (int bj = 0; bj < 2; ++bj) { const u32x4 x = xv[m][bj];
;                         const f32x4 xa = (f32x4){bflo(x.x), bfhi(x.x), bflo(x.y), bfhi(x.y)} + acc[ai][bj][m][0] * scale, xb = (f32x4){bflo(x.z), bfhi(x.z), bflo(x.w), bfhi(x.w)} + acc[ai][bj][m][1] * scale;
;                         *(u32x4*)(XH + (size_t)row * DM + col0 + bj * 128) = pack8(xa, xb);
;                         ssq += ((xa[0] * xa[0] + xa[1] * xa[1]) + (xa[2] * xa[2] + xa[3] * xa[3])) + ((xb[0] * xb[0] + xb[1] * xb[1]) + (xb[2] * xb[2] + xb[3] * xb[3])); }
;                     ssq += __shfl_xor(ssq, 16); ssq += __shfl_xor(ssq, 32);
;                     if (fq == 0) SSP[(size_t)row * 16 + u.pn * 4 + wc] = ssq; }
.LBB0_425:
	s_or_b64 exec, exec, s[18:19]
	v_add_u32_e32 v108, 0x80, v174
	v_ashrrev_i32_e32 v109, 31, v108
	s_waitcnt lgkmcnt(0)
	v_lshlrev_b64 v[68:69], 11, v[108:109]
	v_lshl_add_u64 v[110:111], v[176:177], 0, v[68:69]
	s_nop 1
	v_mov_b64_e32 v[112:113], v[208:209]
	v_mov_b64_e32 v[114:115], v[210:211]
	v_mov_b64_e32 v[92:93], v[212:213]
	v_mov_b64_e32 v[94:95], v[214:215]
	v_add_u32_e32 v104, 0x90, v174
	v_ashrrev_i32_e32 v105, 31, v104
	v_add_u32_e32 v100, 0xa0, v174
	v_lshlrev_b64 v[68:69], 11, v[104:105]
	v_ashrrev_i32_e32 v101, 31, v100
	v_add_u32_e32 v96, 0xb0, v174
	v_lshl_add_u64 v[106:107], v[176:177], 0, v[68:69]
	v_lshlrev_b64 v[68:69], 11, v[100:101]
	v_ashrrev_i32_e32 v97, 31, v96
	v_lshl_add_u64 v[102:103], v[176:177], 0, v[68:69]
	v_lshlrev_b64 v[68:69], 11, v[96:97]
	v_lshl_add_u64 v[98:99], v[176:177], 0, v[68:69]
	v_mov_b64_e32 v[88:89], v[216:217]
	v_mov_b64_e32 v[90:91], v[218:219]
	v_mov_b64_e32 v[84:85], v[220:221]
	v_mov_b64_e32 v[86:87], v[222:223]
	v_mov_b64_e32 v[80:81], v[224:225]
	v_mov_b64_e32 v[82:83], v[226:227]
	v_mov_b64_e32 v[76:77], v[228:229]
	v_mov_b64_e32 v[78:79], v[230:231]
	v_mov_b64_e32 v[72:73], v[232:233]
	v_mov_b64_e32 v[74:75], v[234:235]
	v_mov_b64_e32 v[68:69], v[236:237]
	v_mov_b64_e32 v[70:71], v[238:239]
	v_lshlrev_b32_e32 v116, 16, v112
	v_and_b32_e32 v117, 0xffff0000, v112
	v_lshlrev_b32_e32 v112, 16, v113
	v_and_b32_e32 v113, 0xffff0000, v113
	v_pk_fma_f32 v[66:67], v[66:67], 0.5, v[112:113] op_sel_hi:[1,0,1]
	v_lshlrev_b32_e32 v112, 16, v114
	v_and_b32_e32 v113, 0xffff0000, v114
	v_lshlrev_b32_e32 v114, 16, v115
	v_and_b32_e32 v115, 0xffff0000, v115
	v_pk_fma_f32 v[64:65], v[64:65], 0.5, v[116:117] op_sel_hi:[1,0,1]
	v_pk_fma_f32 v[114:115], v[62:63], 0.5, v[114:115] op_sel_hi:[1,0,1]
	v_pk_fma_f32 v[112:113], v[60:61], 0.5, v[112:113] op_sel_hi:[1,0,1]
	v_cvt_pk_bf16_f32 v60, v64, v65
	v_cvt_pk_bf16_f32 v61, v66, v67
	v_cvt_pk_bf16_f32 v62, v112, v113
	v_cvt_pk_bf16_f32 v63, v114, v115
	global_store_dwordx4 v[110:111], v[60:63], off
	s_nop 1
	v_mul_f32_e32 v60, v65, v65
	v_mul_f32_e32 v61, v67, v67
	v_fmac_f32_e32 v60, v64, v64
	v_fmac_f32_e32 v61, v66, v66
	v_add_f32_e32 v60, v60, v61
	v_mul_f32_e32 v61, v113, v113
	v_mul_f32_e32 v62, v115, v115
	v_fmac_f32_e32 v61, v112, v112
	v_fmac_f32_e32 v62, v114, v114
	v_add_f32_e32 v61, v61, v62
	v_add_f32_e32 v64, v60, v61
	v_lshlrev_b32_e32 v60, 16, v92
	v_and_b32_e32 v61, 0xffff0000, v92
	v_lshlrev_b32_e32 v62, 16, v93
	v_and_b32_e32 v63, 0xffff0000, v93
	v_pk_fma_f32 v[58:59], v[58:59], 0.5, v[62:63] op_sel_hi:[1,0,1]
	v_pk_fma_f32 v[56:57], v[56:57], 0.5, v[60:61] op_sel_hi:[1,0,1]
	v_lshlrev_b32_e32 v60, 16, v94
	v_and_b32_e32 v61, 0xffff0000, v94
	v_lshlrev_b32_e32 v62, 16, v95
	v_and_b32_e32 v63, 0xffff0000, v95
	v_pk_fma_f32 v[62:63], v[54:55], 0.5, v[62:63] op_sel_hi:[1,0,1]
	v_pk_fma_f32 v[60:61], v[52:53], 0.5, v[60:61] op_sel_hi:[1,0,1]
	v_cvt_pk_bf16_f32 v52, v56, v57
	v_cvt_pk_bf16_f32 v53, v58, v59
	v_cvt_pk_bf16_f32 v54, v60, v61
	v_cvt_pk_bf16_f32 v55, v62, v63
	global_store_dwordx4 v[110:111], v[52:55], off offset:256
	s_nop 1
	v_mul_f32_e32 v52, v57, v57
	v_mul_f32_e32 v53, v59, v59
	v_fmac_f32_e32 v52, v56, v56
	v_fmac_f32_e32 v53, v58, v58
	v_add_f32_e32 v52, v52, v53
	v_mul_f32_e32 v53, v61, v61
	v_mul_f32_e32 v54, v63, v63
	v_fmac_f32_e32 v53, v60, v60
	v_fmac_f32_e32 v54, v62, v62
	v_add_f32_e32 v53, v53, v54
	v_add_f32_e32 v52, v52, v53
	v_add_f32_e32 v52, v64, v52
	ds_bpermute_b32 v53, v195, v52
	s_waitcnt lgkmcnt(0)
	v_add_f32_e32 v52, v52, v53
	ds_bpermute_b32 v53, v194, v52
	s_and_saveexec_b64 s[18:19], s[2:3]
	s_cbranch_execz .LBB0_427
	s_waitcnt lgkmcnt(0)
	v_add_f32_e32 v54, v52, v53
	s_lshl_b32 s20, s37, 2
	v_lshlrev_b64 v[52:53], 6, v[108:109]
	s_ashr_i32 s21, s20, 31
	v_lshl_add_u64 v[52:53], s[10:11], 0, v[52:53]
	v_lshl_add_u64 v[52:53], s[20:21], 2, v[52:53]
	s_lshl_b32 s62, s43, 2
	v_lshl_add_u64 v[52:53], v[52:53], 0, s[62:63]
	global_store_dword v[52:53], v54, off
.LBB0_427:
	s_or_b64 exec, exec, s[18:19]
	v_lshlrev_b32_e32 v52, 16, v88
	s_waitcnt lgkmcnt(0)
	v_and_b32_e32 v53, 0xffff0000, v88
	v_lshlrev_b32_e32 v54, 16, v89
	v_and_b32_e32 v55, 0xffff0000, v89
	v_pk_fma_f32 v[50:51], v[50:51], 0.5, v[54:55] op_sel_hi:[1,0,1]
	v_pk_fma_f32 v[48:49], v[48:49], 0.5, v[52:53] op_sel_hi:[1,0,1]
	v_lshlrev_b32_e32 v52, 16, v90
	v_and_b32_e32 v53, 0xffff0000, v90
	v_lshlrev_b32_e32 v54, 16, v91
	v_and_b32_e32 v55, 0xffff0000, v91
	v_pk_fma_f32 v[54:55], v[46:47], 0.5, v[54:55] op_sel_hi:[1,0,1]
	v_pk_fma_f32 v[46:47], v[44:45], 0.5, v[52:53] op_sel_hi:[1,0,1]
	v_cvt_pk_bf16_f32 v44, v48, v49
	v_mul_f32_e32 v49, v49, v49
	v_fmac_f32_e32 v49, v48, v48
	v_mul_f32_e32 v48, v51, v51
	v_fmac_f32_e32 v48, v50, v50
	v_cvt_pk_bf16_f32 v45, v50, v51
	v_add_f32_e32 v48, v49, v48
	v_mul_f32_e32 v49, v47, v47
	v_mul_f32_e32 v50, v55, v55
	v_fmac_f32_e32 v49, v46, v46
	v_fmac_f32_e32 v50, v54, v54
	v_add_f32_e32 v49, v49, v50
	v_add_f32_e32 v52, v48, v49
	v_lshlrev_b32_e32 v48, 16, v84
	v_and_b32_e32 v49, 0xffff0000, v84
	v_lshlrev_b32_e32 v50, 16, v85
	v_and_b32_e32 v51, 0xffff0000, v85
	v_pk_fma_f32 v[42:43], v[42:43], 0.5, v[50:51] op_sel_hi:[1,0,1]
	v_pk_fma_f32 v[40:41], v[40:41], 0.5, v[48:49] op_sel_hi:[1,0,1]
	v_lshlrev_b32_e32 v48, 16, v86
	v_and_b32_e32 v49, 0xffff0000, v86
	v_lshlrev_b32_e32 v50, 16, v87
	v_and_b32_e32 v51, 0xffff0000, v87
	v_pk_fma_f32 v[48:49], v[36:37], 0.5, v[48:49] op_sel_hi:[1,0,1]
	v_mul_f32_e32 v36, v41, v41
	v_mul_f32_e32 v37, v43, v43
	v_pk_fma_f32 v[50:51], v[38:39], 0.5, v[50:51] op_sel_hi:[1,0,1]
	v_fmac_f32_e32 v36, v40, v40
	v_fmac_f32_e32 v37, v42, v42
	v_add_f32_e32 v36, v36, v37
	v_mul_f32_e32 v37, v49, v49
	v_mul_f32_e32 v38, v51, v51
	v_fmac_f32_e32 v37, v48, v48
	v_fmac_f32_e32 v38, v50, v50
	v_add_f32_e32 v37, v37, v38
	v_add_f32_e32 v36, v36, v37
	v_add_f32_e32 v36, v52, v36
	ds_bpermute_b32 v37, v195, v36
	v_cvt_pk_bf16_f32 v46, v46, v47
	v_cvt_pk_bf16_f32 v47, v54, v55
	v_cvt_pk_bf16_f32 v38, v40, v41
	v_cvt_pk_bf16_f32 v39, v42, v43
	s_waitcnt lgkmcnt(0)
	v_add_f32_e32 v36, v36, v37
	ds_bpermute_b32 v37, v194, v36
	v_cvt_pk_bf16_f32 v40, v48, v49
	v_cvt_pk_bf16_f32 v41, v50, v51
	global_store_dwordx4 v[106:107], v[44:47], off
	global_store_dwordx4 v[106:107], v[38:41], off offset:256
	s_and_saveexec_b64 s[18:19], s[2:3]
	s_cbranch_execz .LBB0_429
	s_waitcnt lgkmcnt(0)
	v_add_f32_e32 v38, v36, v37
	s_lshl_b32 s20, s37, 2
	v_lshlrev_b64 v[36:37], 6, v[104:105]
	s_ashr_i32 s21, s20, 31
	v_lshl_add_u64 v[36:37], s[10:11], 0, v[36:37]
	v_lshl_add_u64 v[36:37], s[20:21], 2, v[36:37]
	s_lshl_b32 s62, s43, 2
	v_lshl_add_u64 v[36:37], v[36:37], 0, s[62:63]
	global_store_dword v[36:37], v38, off
; DI u32x4 pack8(f32x4 a, f32x4 b) { u32x4 w; w.x = pk2(a[0], a[1]); w.y = pk2(a[2], a[3]); w.z = pk2(b[0], b[1]); w.w = pk2(b[2], b[3]); return w; }
;     DI void operator()(const pg8::Acc& acc, const pg8::Unit& u, int wr, int wc, int fr, int fq) const {
;     ...
;                 for (int m = 0; m < 4; ++m) { const int row = row0 + ai * 128 + m * 16; float ssq = 0.f;
; #pragma unroll
;                     for (int bj = 0; bj < 2; ++bj) { const u32x4 x = xv[m][bj];
;                         const f32x4 xa = (f32x4){bflo(x.x), bfhi(x.x), bflo(x.y), bfhi(x.y)} + acc[ai][bj][m][0] * scale, xb = (f32x4){bflo(x.z), bfhi(x.z), bflo(x.w), bfhi(x.w)} + acc[ai][bj][m][1] * scale;
;                         *(u32x4*)(XH + (size_t)row * DM + col0 + bj * 128) = pack8(xa, xb);
;                         ssq += ((xa[0] * xa[0] + xa[1] * xa[1]) + (xa[2] * xa[2] + xa[3] * xa[3])) + ((xb[0] * xb[0] + xb[1] * xb[1]) + (xb[2] * xb[2] + xb[3] * xb[3])); }
;                     ssq += __shfl_xor(ssq, 16); ssq += __shfl_xor(ssq, 32);
;                     if (fq == 0) SSP[(size_t)row * 16 + u.pn * 4 + wc] = ssq; }
.LBB0_429:
	s_or_b64 exec, exec, s[18:19]
	v_lshlrev_b32_e32 v36, 16, v80
	s_waitcnt lgkmcnt(0)
	v_and_b32_e32 v37, 0xffff0000, v80
	v_lshlrev_b32_e32 v38, 16, v81
	v_and_b32_e32 v39, 0xffff0000, v81
	v_pk_fma_f32 v[34:35], v[34:35], 0.5, v[38:39] op_sel_hi:[1,0,1]
	v_pk_fma_f32 v[32:33], v[32:33], 0.5, v[36:37] op_sel_hi:[1,0,1]
	v_lshlrev_b32_e32 v36, 16, v82
	v_and_b32_e32 v37, 0xffff0000, v82
	v_lshlrev_b32_e32 v38, 16, v83
	v_and_b32_e32 v39, 0xffff0000, v83
	v_pk_fma_f32 v[38:39], v[30:31], 0.5, v[38:39] op_sel_hi:[1,0,1]
	v_pk_fma_f32 v[30:31], v[28:29], 0.5, v[36:37] op_sel_hi:[1,0,1]
	v_cvt_pk_bf16_f32 v28, v32, v33
	v_mul_f32_e32 v33, v33, v33
	v_fmac_f32_e32 v33, v32, v32
	v_mul_f32_e32 v32, v35, v35
	v_fmac_f32_e32 v32, v34, v34
	v_cvt_pk_bf16_f32 v29, v34, v35
	v_add_f32_e32 v32, v33, v32
	v_mul_f32_e32 v33, v31, v31
	v_mul_f32_e32 v34, v39, v39
	v_fmac_f32_e32 v33, v30, v30
	v_fmac_f32_e32 v34, v38, v38
	v_add_f32_e32 v33, v33, v34
	v_add_f32_e32 v36, v32, v33
	v_lshlrev_b32_e32 v32, 16, v76
	v_and_b32_e32 v33, 0xffff0000, v76
	v_lshlrev_b32_e32 v34, 16, v77
	v_and_b32_e32 v35, 0xffff0000, v77
	v_pk_fma_f32 v[26:27], v[26:27], 0.5, v[34:35] op_sel_hi:[1,0,1]
	v_pk_fma_f32 v[24:25], v[24:25], 0.5, v[32:33] op_sel_hi:[1,0,1]
	v_lshlrev_b32_e32 v32, 16, v78
	v_and_b32_e32 v33, 0xffff0000, v78
	v_lshlrev_b32_e32 v34, 16, v79
	v_and_b32_e32 v35, 0xffff0000, v79
	v_pk_fma_f32 v[32:33], v[20:21], 0.5, v[32:33] op_sel_hi:[1,0,1]
	v_mul_f32_e32 v20, v25, v25
	v_mul_f32_e32 v21, v27, v27
	v_pk_fma_f32 v[34:35], v[22:23], 0.5, v[34:35] op_sel_hi:[1,0,1]
	v_fmac_f32_e32 v20, v24, v24
	v_fmac_f32_e32 v21, v26, v26
	v_add_f32_e32 v20, v20, v21
	v_mul_f32_e32 v21, v33, v33
	v_mul_f32_e32 v22, v35, v35
	v_fmac_f32_e32 v21, v32, v32
	v_fmac_f32_e32 v22, v34, v34
	v_add_f32_e32 v21, v21, v22
	v_add_f32_e32 v20, v20, v21
	v_add_f32_e32 v20, v36, v20
	ds_bpermute_b32 v21, v195, v20
	v_cvt_pk_bf16_f32 v30, v30, v31
	v_cvt_pk_bf16_f32 v31, v38, v39
	v_cvt_pk_bf16_f32 v22, v24, v25
	v_cvt_pk_bf16_f32 v23, v26, v27
	s_waitcnt lgkmcnt(0)
	v_add_f32_e32 v20, v20, v21
	ds_bpermute_b32 v21, v194, v20
	v_cvt_pk_bf16_f32 v24, v32, v33
	v_cvt_pk_bf16_f32 v25, v34, v35
	global_store_dwordx4 v[102:103], v[28:31], off
	global_store_dwordx4 v[102:103], v[22:25], off offset:256
	s_and_saveexec_b64 s[18:19], s[2:3]
	s_cbranch_execz .LBB0_431
	s_waitcnt lgkmcnt(0)
	v_add_f32_e32 v22, v20, v21
	s_lshl_b32 s20, s37, 2
	v_lshlrev_b64 v[20:21], 6, v[100:101]
	s_ashr_i32 s21, s20, 31
	v_lshl_add_u64 v[20:21], s[10:11], 0, v[20:21]
	v_lshl_add_u64 v[20:21], s[20:21], 2, v[20:21]
	s_lshl_b32 s62, s43, 2
	v_lshl_add_u64 v[20:21], v[20:21], 0, s[62:63]
	global_store_dword v[20:21], v22, off
.LBB0_431:
	s_or_b64 exec, exec, s[18:19]
	v_lshlrev_b32_e32 v20, 16, v72
	s_waitcnt lgkmcnt(0)
	v_and_b32_e32 v21, 0xffff0000, v72
	v_lshlrev_b32_e32 v22, 16, v73
	v_and_b32_e32 v23, 0xffff0000, v73
	v_pk_fma_f32 v[18:19], v[18:19], 0.5, v[22:23] op_sel_hi:[1,0,1]
	v_pk_fma_f32 v[16:17], v[16:17], 0.5, v[20:21] op_sel_hi:[1,0,1]
	v_lshlrev_b32_e32 v20, 16, v74
	v_and_b32_e32 v21, 0xffff0000, v74
	v_lshlrev_b32_e32 v22, 16, v75
	v_and_b32_e32 v23, 0xffff0000, v75
	v_pk_fma_f32 v[22:23], v[14:15], 0.5, v[22:23] op_sel_hi:[1,0,1]
	v_pk_fma_f32 v[14:15], v[12:13], 0.5, v[20:21] op_sel_hi:[1,0,1]
	v_cvt_pk_bf16_f32 v12, v16, v17
	v_mul_f32_e32 v17, v17, v17
	v_fmac_f32_e32 v17, v16, v16
	v_mul_f32_e32 v16, v19, v19
	v_fmac_f32_e32 v16, v18, v18
	v_cvt_pk_bf16_f32 v13, v18, v19
	v_add_f32_e32 v16, v17, v16
	v_mul_f32_e32 v17, v15, v15
	v_mul_f32_e32 v18, v23, v23
	v_fmac_f32_e32 v17, v14, v14
	v_fmac_f32_e32 v18, v22, v22
	v_add_f32_e32 v17, v17, v18
	v_add_f32_e32 v20, v16, v17
	v_lshlrev_b32_e32 v16, 16, v68
	v_and_b32_e32 v17, 0xffff0000, v68
	v_lshlrev_b32_e32 v18, 16, v69
	v_and_b32_e32 v19, 0xffff0000, v69
	v_pk_fma_f32 v[10:11], v[10:11], 0.5, v[18:19] op_sel_hi:[1,0,1]
	v_pk_fma_f32 v[8:9], v[8:9], 0.5, v[16:17] op_sel_hi:[1,0,1]
	v_lshlrev_b32_e32 v16, 16, v70
	v_and_b32_e32 v17, 0xffff0000, v70
	v_lshlrev_b32_e32 v18, 16, v71
	v_and_b32_e32 v19, 0xffff0000, v71
	v_pk_fma_f32 v[16:17], v[4:5], 0.5, v[16:17] op_sel_hi:[1,0,1]
	v_mul_f32_e32 v4, v9, v9
	v_mul_f32_e32 v5, v11, v11
	v_pk_fma_f32 v[18:19], v[6:7], 0.5, v[18:19] op_sel_hi:[1,0,1]
	v_fmac_f32_e32 v4, v8, v8
	v_fmac_f32_e32 v5, v10, v10
	v_add_f32_e32 v4, v4, v5
	v_mul_f32_e32 v5, v17, v17
	v_mul_f32_e32 v6, v19, v19
	v_fmac_f32_e32 v5, v16, v16
	v_fmac_f32_e32 v6, v18, v18
	v_add_f32_e32 v5, v5, v6
	v_add_f32_e32 v4, v4, v5
	v_add_f32_e32 v4, v20, v4
	ds_bpermute_b32 v5, v195, v4
	v_cvt_pk_bf16_f32 v14, v14, v15
	v_cvt_pk_bf16_f32 v15, v22, v23
	v_cvt_pk_bf16_f32 v6, v8, v9
	v_cvt_pk_bf16_f32 v7, v10, v11
	s_waitcnt lgkmcnt(0)
	v_add_f32_e32 v4, v4, v5
	ds_bpermute_b32 v5, v194, v4
	v_cvt_pk_bf16_f32 v8, v16, v17
	v_cvt_pk_bf16_f32 v9, v18, v19
	global_store_dwordx4 v[98:99], v[12:15], off
	global_store_dwordx4 v[98:99], v[6:9], off offset:256
	s_and_saveexec_b64 s[18:19], s[2:3]
	s_cbranch_execz .LBB0_433
	s_waitcnt lgkmcnt(0)
	v_add_f32_e32 v6, v4, v5
	s_lshl_b32 s20, s37, 2
	v_lshlrev_b64 v[4:5], 6, v[96:97]
	s_ashr_i32 s21, s20, 31
	v_lshl_add_u64 v[4:5], s[10:11], 0, v[4:5]
	v_lshl_add_u64 v[4:5], s[20:21], 2, v[4:5]
	s_lshl_b32 s62, s43, 2
	v_lshl_add_u64 v[4:5], v[4:5], 0, s[62:63]
	global_store_dword v[4:5], v6, off

; DI u32x4 pack8(f32x4 a, f32x4 b) { u32x4 w; w.x = pk2(a[0], a[1]); w.y = pk2(a[2], a[3]); w.z = pk2(b[0], b[1]); w.w = pk2(b[2], b[3]); return w; }
;     DI void operator()(const pg8::Acc& acc, const pg8::Unit& u, int wr, int wc, int fr, int fq) const {
;         const int row0 = u.pm * 256 + wr * 64 + fr, col0 = u.pn * 256 + wc * 32 + 8 * fq;
;         if (u.kind == 0) {
;             float* X = (float*)(ws + WS_X); float* SSP = (float*)(ws + WS_SSP) + (size_t)site * MT * 16;
; #pragma unroll
;             for (int ai = 0; ai < 2; ++ai) {
;                 bf16* XH = (bf16*)X;
;                 u32x4 xv[4][2];
; #pragma unroll
;                 for (int m = 0; m < 4; ++m)
; #pragma unroll
;                     for (int bj = 0; bj < 2; ++bj) xv[m][bj] = *(const u32x4*)(XH + (size_t)(row0 + ai * 128 + m * 16) * DM + col0 + bj * 128);
; #pragma unroll
;                 for (int m = 0; m < 4; ++m) { const int row = row0 + ai * 128 + m * 16; float ssq = 0.f;
; #pragma unroll
;                     for (int bj = 0; bj < 2; ++bj) { const u32x4 x = xv[m][bj];
;                         const f32x4 xa = (f32x4){bflo(x.x), bfhi(x.x), bflo(x.y), bfhi(x.y)} + acc[ai][bj][m][0] * scale, xb = (f32x4){bflo(x.z), bfhi(x.z), bflo(x.w), bfhi(x.w)} + acc[ai][bj][m][1] * scale;
;                         *(u32x4*)(XH + (size_t)row * DM + col0 + bj * 128) = pack8(xa, xb);
;                         ssq += ((xa[0] * xa[0] + xa[1] * xa[1]) + (xa[2] * xa[2] + xa[3] * xa[3])) + ((xb[0] * xb[0] + xb[1] * xb[1]) + (xb[2] * xb[2] + xb[3] * xb[3])); }
;                     ssq += __shfl_xor(ssq, 16); ssq += __shfl_xor(ssq, 32);
;                     if (fq == 0) SSP[(size_t)row * 16 + u.pn * 4 + wc] = ssq; }
.LBB0_1770:
	v_lshl_add_u64 v[176:177], v[132:133], 1, s[8:9]
	v_and_b32_e32 v133, 64, v198
	v_xor_b32_e32 v132, 16, v198
	v_add_u32_e32 v133, 64, v133
	v_cmp_lt_i32_e32 vcc, v132, v133
	v_or_b32_e32 v186, 16, v174
	v_ashrrev_i32_e32 v187, 31, v186
	v_cndmask_b32_e32 v132, v198, v132, vcc
	v_lshlrev_b32_e32 v195, 2, v132
	v_xor_b32_e32 v132, 32, v198
	v_cmp_lt_i32_e32 vcc, v132, v133
	v_or_b32_e32 v182, 32, v174
	v_ashrrev_i32_e32 v183, 31, v182
	v_cndmask_b32_e32 v132, v198, v132, vcc
	v_lshlrev_b32_e32 v194, 2, v132
	v_lshlrev_b64 v[132:133], 11, v[174:175]
	v_lshl_add_u64 v[190:191], v[176:177], 0, v[132:133]
	global_load_dwordx4 v[202:205], v[190:191], off
	global_load_dwordx4 v[156:159], v[190:191], off offset:256
	v_lshlrev_b64 v[132:133], 11, v[186:187]
	v_or_b32_e32 v178, 48, v174
	v_lshl_add_u64 v[188:189], v[176:177], 0, v[132:133]
	v_lshlrev_b64 v[132:133], 11, v[182:183]
	v_ashrrev_i32_e32 v179, 31, v178
	v_lshl_add_u64 v[184:185], v[176:177], 0, v[132:133]
	v_lshlrev_b64 v[132:133], 11, v[178:179]
	v_lshl_add_u64 v[180:181], v[176:177], 0, v[132:133]
	global_load_dwordx4 v[152:155], v[188:189], off
	global_load_dwordx4 v[148:151], v[188:189], off offset:256
	global_load_dwordx4 v[144:147], v[184:185], off
	global_load_dwordx4 v[140:143], v[184:185], off offset:256
	global_load_dwordx4 v[136:139], v[180:181], off
	global_load_dwordx4 v[132:135], v[180:181], off offset:256
	v_lshl_add_u64 v[240:241], s[88:89], 1, v[190:191]
	v_lshl_add_u64 v[242:243], s[88:89], 1, v[188:189]
	v_lshl_add_u64 v[244:245], s[88:89], 1, v[184:185]
	v_lshl_add_u64 v[246:247], s[88:89], 1, v[180:181]
	global_load_dwordx4 v[208:211], v[240:241], off
	global_load_dwordx4 v[212:215], v[240:241], off offset:256
	global_load_dwordx4 v[216:219], v[242:243], off
	global_load_dwordx4 v[220:223], v[242:243], off offset:256
	global_load_dwordx4 v[224:227], v[244:245], off
	global_load_dwordx4 v[228:231], v[244:245], off offset:256
	global_load_dwordx4 v[232:235], v[246:247], off
	global_load_dwordx4 v[236:239], v[246:247], off offset:256
	s_waitcnt vmcnt(0)
	v_lshlrev_b32_e32 v206, 16, v202
	v_and_b32_e32 v207, 0xffff0000, v202
	v_lshlrev_b32_e32 v202, 16, v203
	v_and_b32_e32 v203, 0xffff0000, v203
	v_pk_add_f32 v[130:131], v[130:131], v[202:203]
	v_lshlrev_b32_e32 v202, 16, v204
	v_and_b32_e32 v203, 0xffff0000, v204
	v_lshlrev_b32_e32 v204, 16, v205
	v_and_b32_e32 v205, 0xffff0000, v205
	v_pk_add_f32 v[128:129], v[128:129], v[206:207]
	v_pk_add_f32 v[204:205], v[126:127], v[204:205]
	v_pk_add_f32 v[202:203], v[124:125], v[202:203]
	v_cvt_pk_bf16_f32 v124, v128, v129
	v_cvt_pk_bf16_f32 v125, v130, v131
	v_cvt_pk_bf16_f32 v126, v202, v203
	v_cvt_pk_bf16_f32 v127, v204, v205
	global_store_dwordx4 v[190:191], v[124:127], off
	s_nop 1
	v_mul_f32_e32 v124, v129, v129
	v_mul_f32_e32 v125, v131, v131
	v_fmac_f32_e32 v124, v128, v128
	v_fmac_f32_e32 v125, v130, v130
	v_add_f32_e32 v124, v124, v125
	v_mul_f32_e32 v125, v203, v203
	v_mul_f32_e32 v126, v205, v205
	v_fmac_f32_e32 v125, v202, v202
	v_fmac_f32_e32 v126, v204, v204
	v_add_f32_e32 v125, v125, v126
	v_add_f32_e32 v128, v124, v125
	v_lshlrev_b32_e32 v124, 16, v156
	v_and_b32_e32 v125, 0xffff0000, v156
	v_lshlrev_b32_e32 v126, 16, v157
	v_and_b32_e32 v127, 0xffff0000, v157
	v_pk_add_f32 v[122:123], v[122:123], v[126:127]
	v_pk_add_f32 v[120:121], v[120:121], v[124:125]
	v_lshlrev_b32_e32 v124, 16, v158
	v_and_b32_e32 v125, 0xffff0000, v158
	v_lshlrev_b32_e32 v126, 16, v159
	v_and_b32_e32 v127, 0xffff0000, v159
	v_pk_add_f32 v[126:127], v[118:119], v[126:127]
	v_pk_add_f32 v[124:125], v[116:117], v[124:125]
	v_cvt_pk_bf16_f32 v116, v120, v121
	v_cvt_pk_bf16_f32 v117, v122, v123
	v_cvt_pk_bf16_f32 v118, v124, v125
	v_cvt_pk_bf16_f32 v119, v126, v127
	global_store_dwordx4 v[190:191], v[116:119], off offset:256
	s_nop 1
	v_mul_f32_e32 v116, v121, v121
	v_mul_f32_e32 v117, v123, v123
	v_fmac_f32_e32 v116, v120, v120
	v_fmac_f32_e32 v117, v122, v122
	v_add_f32_e32 v116, v116, v117
	v_mul_f32_e32 v117, v125, v125
	v_mul_f32_e32 v118, v127, v127
	v_fmac_f32_e32 v117, v124, v124
	v_fmac_f32_e32 v118, v126, v126
	v_add_f32_e32 v117, v117, v118
	v_add_f32_e32 v116, v116, v117
	v_add_f32_e32 v116, v128, v116
	ds_bpermute_b32 v117, v195, v116
	s_waitcnt lgkmcnt(0)
	v_add_f32_e32 v116, v116, v117
	ds_bpermute_b32 v117, v194, v116
	s_and_saveexec_b64 s[20:21], s[2:3]
	s_cbranch_execz .LBB0_1772
	s_waitcnt lgkmcnt(0)
	v_add_f32_e32 v118, v116, v117
	s_lshl_b32 s22, s39, 2
	v_lshlrev_b64 v[116:117], 6, v[174:175]
	s_ashr_i32 s23, s22, 31
	v_lshl_add_u64 v[116:117], s[10:11], 0, v[116:117]
	v_lshl_add_u64 v[116:117], s[22:23], 2, v[116:117]
	s_lshl_b32 s62, s45, 2
	v_lshl_add_u64 v[116:117], v[116:117], 0, s[62:63]
	global_store_dword v[116:117], v118, off

; DI u32x4 pack8(f32x4 a, f32x4 b) { u32x4 w; w.x = pk2(a[0], a[1]); w.y = pk2(a[2], a[3]); w.z = pk2(b[0], b[1]); w.w = pk2(b[2], b[3]); return w; }
;     DI void operator()(const pg8::Acc& acc, const pg8::Unit& u, int wr, int wc, int fr, int fq) const {
;     ...
;             float* X = (float*)(ws + WS_X); float* SSP = (float*)(ws + WS_SSP) + (size_t)site * MT * 16;
; #pragma unroll
;             for (int ai = 0; ai < 2; ++ai) {
;                 bf16* XH = (bf16*)X;
;                 u32x4 xv[4][2];
; #pragma unroll
;                 for (int m = 0; m < 4; ++m)
; #pragma unroll
;                     for (int bj = 0; bj < 2; ++bj) xv[m][bj] = *(const u32x4*)(XH + (size_t)(row0 + ai * 128 + m * 16) * DM + col0 + bj * 128);
; #pragma unroll
;                 for (int m = 0; m < 4; ++m) { const int row = row0 + ai * 128 + m * 16; float ssq = 0.f;
; #pragma unroll
;                     for (int bj = 0; bj < 2; ++bj) { const u32x4 x = xv[m][bj];
;                         const f32x4 xa = (f32x4){bflo(x.x), bfhi(x.x), bflo(x.y), bfhi(x.y)} + acc[ai][bj][m][0] * scale, xb = (f32x4){bflo(x.z), bfhi(x.z), bflo(x.w), bfhi(x.w)} + acc[ai][bj][m][1] * scale;
;                         *(u32x4*)(XH + (size_t)row * DM + col0 + bj * 128) = pack8(xa, xb);
;                         ssq += ((xa[0] * xa[0] + xa[1] * xa[1]) + (xa[2] * xa[2] + xa[3] * xa[3])) + ((xb[0] * xb[0] + xb[1] * xb[1]) + (xb[2] * xb[2] + xb[3] * xb[3])); }
;                     ssq += __shfl_xor(ssq, 16); ssq += __shfl_xor(ssq, 32);
;                     if (fq == 0) SSP[(size_t)row * 16 + u.pn * 4 + wc] = ssq; }
.LBB0_1778:
	s_or_b64 exec, exec, s[20:21]
	v_add_u32_e32 v108, 0x80, v174
	v_ashrrev_i32_e32 v109, 31, v108
	s_waitcnt lgkmcnt(0)
	v_lshlrev_b64 v[68:69], 11, v[108:109]
	v_lshl_add_u64 v[110:111], v[176:177], 0, v[68:69]
	s_nop 1
	v_mov_b64_e32 v[112:113], v[208:209]
	v_mov_b64_e32 v[114:115], v[210:211]
	v_mov_b64_e32 v[92:93], v[212:213]
	v_mov_b64_e32 v[94:95], v[214:215]
	v_add_u32_e32 v104, 0x90, v174
	v_ashrrev_i32_e32 v105, 31, v104
	v_add_u32_e32 v100, 0xa0, v174
	v_lshlrev_b64 v[68:69], 11, v[104:105]
	v_ashrrev_i32_e32 v101, 31, v100
	v_add_u32_e32 v96, 0xb0, v174
	v_lshl_add_u64 v[106:107], v[176:177], 0, v[68:69]
	v_lshlrev_b64 v[68:69], 11, v[100:101]
	v_ashrrev_i32_e32 v97, 31, v96
	v_lshl_add_u64 v[102:103], v[176:177], 0, v[68:69]
	v_lshlrev_b64 v[68:69], 11, v[96:97]
	v_lshl_add_u64 v[98:99], v[176:177], 0, v[68:69]
	v_mov_b64_e32 v[88:89], v[216:217]
	v_mov_b64_e32 v[90:91], v[218:219]
	v_mov_b64_e32 v[84:85], v[220:221]
	v_mov_b64_e32 v[86:87], v[222:223]
	v_mov_b64_e32 v[80:81], v[224:225]
	v_mov_b64_e32 v[82:83], v[226:227]
	v_mov_b64_e32 v[76:77], v[228:229]
	v_mov_b64_e32 v[78:79], v[230:231]
	v_mov_b64_e32 v[72:73], v[232:233]
	v_mov_b64_e32 v[74:75], v[234:235]
	v_mov_b64_e32 v[68:69], v[236:237]
	v_mov_b64_e32 v[70:71], v[238:239]
	v_lshlrev_b32_e32 v116, 16, v112
	v_and_b32_e32 v117, 0xffff0000, v112
	v_lshlrev_b32_e32 v112, 16, v113
	v_and_b32_e32 v113, 0xffff0000, v113
	v_pk_add_f32 v[66:67], v[66:67], v[112:113]
	v_lshlrev_b32_e32 v112, 16, v114
	v_and_b32_e32 v113, 0xffff0000, v114
	v_lshlrev_b32_e32 v114, 16, v115
	v_and_b32_e32 v115, 0xffff0000, v115
	v_pk_add_f32 v[64:65], v[64:65], v[116:117]
	v_pk_add_f32 v[114:115], v[62:63], v[114:115]
	v_pk_add_f32 v[112:113], v[60:61], v[112:113]
	v_cvt_pk_bf16_f32 v60, v64, v65
	v_cvt_pk_bf16_f32 v61, v66, v67
	v_cvt_pk_bf16_f32 v62, v112, v113
	v_cvt_pk_bf16_f32 v63, v114, v115
	global_store_dwordx4 v[110:111], v[60:63], off
	s_nop 1
	v_mul_f32_e32 v60, v65, v65
	v_mul_f32_e32 v61, v67, v67
	v_fmac_f32_e32 v60, v64, v64
	v_fmac_f32_e32 v61, v66, v66
	v_add_f32_e32 v60, v60, v61
	v_mul_f32_e32 v61, v113, v113
	v_mul_f32_e32 v62, v115, v115
	v_fmac_f32_e32 v61, v112, v112
	v_fmac_f32_e32 v62, v114, v114
	v_add_f32_e32 v61, v61, v62
	v_add_f32_e32 v64, v60, v61
	v_lshlrev_b32_e32 v60, 16, v92
	v_and_b32_e32 v61, 0xffff0000, v92
	v_lshlrev_b32_e32 v62, 16, v93
	v_and_b32_e32 v63, 0xffff0000, v93
	v_pk_add_f32 v[58:59], v[58:59], v[62:63]
	v_pk_add_f32 v[56:57], v[56:57], v[60:61]
	v_lshlrev_b32_e32 v60, 16, v94
	v_and_b32_e32 v61, 0xffff0000, v94
	v_lshlrev_b32_e32 v62, 16, v95
	v_and_b32_e32 v63, 0xffff0000, v95
	v_pk_add_f32 v[62:63], v[54:55], v[62:63]
	v_pk_add_f32 v[60:61], v[52:53], v[60:61]
	v_cvt_pk_bf16_f32 v52, v56, v57
	v_cvt_pk_bf16_f32 v53, v58, v59
	v_cvt_pk_bf16_f32 v54, v60, v61
	v_cvt_pk_bf16_f32 v55, v62, v63
	global_store_dwordx4 v[110:111], v[52:55], off offset:256
	s_nop 1
	v_mul_f32_e32 v52, v57, v57
	v_mul_f32_e32 v53, v59, v59
	v_fmac_f32_e32 v52, v56, v56
	v_fmac_f32_e32 v53, v58, v58
	v_add_f32_e32 v52, v52, v53
	v_mul_f32_e32 v53, v61, v61
	v_mul_f32_e32 v54, v63, v63
	v_fmac_f32_e32 v53, v60, v60
	v_fmac_f32_e32 v54, v62, v62
	v_add_f32_e32 v53, v53, v54
	v_add_f32_e32 v52, v52, v53
	v_add_f32_e32 v52, v64, v52
	ds_bpermute_b32 v53, v195, v52
	s_waitcnt lgkmcnt(0)
	v_add_f32_e32 v52, v52, v53
	ds_bpermute_b32 v53, v194, v52
	s_and_saveexec_b64 s[20:21], s[2:3]
	s_cbranch_execz .LBB0_1780
	s_waitcnt lgkmcnt(0)
	v_add_f32_e32 v54, v52, v53
	s_lshl_b32 s22, s39, 2
	v_lshlrev_b64 v[52:53], 6, v[108:109]
	s_ashr_i32 s23, s22, 31
	v_lshl_add_u64 v[52:53], s[10:11], 0, v[52:53]
	v_lshl_add_u64 v[52:53], s[22:23], 2, v[52:53]
	s_lshl_b32 s62, s45, 2
	v_lshl_add_u64 v[52:53], v[52:53], 0, s[62:63]
	global_store_dword v[52:53], v54, off
.LBB0_1780:
	s_or_b64 exec, exec, s[20:21]
	v_lshlrev_b32_e32 v52, 16, v88
	s_waitcnt lgkmcnt(0)
	v_and_b32_e32 v53, 0xffff0000, v88
	v_lshlrev_b32_e32 v54, 16, v89
	v_and_b32_e32 v55, 0xffff0000, v89
	v_pk_add_f32 v[50:51], v[50:51], v[54:55]
	v_pk_add_f32 v[48:49], v[48:49], v[52:53]
	v_lshlrev_b32_e32 v52, 16, v90
	v_and_b32_e32 v53, 0xffff0000, v90
	v_lshlrev_b32_e32 v54, 16, v91
	v_and_b32_e32 v55, 0xffff0000, v91
	v_pk_add_f32 v[54:55], v[46:47], v[54:55]
	v_pk_add_f32 v[46:47], v[44:45], v[52:53]
	v_cvt_pk_bf16_f32 v44, v48, v49
	v_mul_f32_e32 v49, v49, v49
	v_fmac_f32_e32 v49, v48, v48
	v_mul_f32_e32 v48, v51, v51
	v_fmac_f32_e32 v48, v50, v50
	v_cvt_pk_bf16_f32 v45, v50, v51
	v_add_f32_e32 v48, v49, v48
	v_mul_f32_e32 v49, v47, v47
	v_mul_f32_e32 v50, v55, v55
	v_fmac_f32_e32 v49, v46, v46
	v_fmac_f32_e32 v50, v54, v54
	v_add_f32_e32 v49, v49, v50
	v_add_f32_e32 v52, v48, v49
	v_lshlrev_b32_e32 v48, 16, v84
	v_and_b32_e32 v49, 0xffff0000, v84
	v_lshlrev_b32_e32 v50, 16, v85
	v_and_b32_e32 v51, 0xffff0000, v85
	v_pk_add_f32 v[42:43], v[42:43], v[50:51]
	v_pk_add_f32 v[40:41], v[40:41], v[48:49]
	v_lshlrev_b32_e32 v48, 16, v86
	v_and_b32_e32 v49, 0xffff0000, v86
	v_lshlrev_b32_e32 v50, 16, v87
	v_and_b32_e32 v51, 0xffff0000, v87
	v_pk_add_f32 v[48:49], v[36:37], v[48:49]
	v_mul_f32_e32 v36, v41, v41
	v_mul_f32_e32 v37, v43, v43
	v_pk_add_f32 v[50:51], v[38:39], v[50:51]
	v_fmac_f32_e32 v36, v40, v40
	v_fmac_f32_e32 v37, v42, v42
	v_add_f32_e32 v36, v36, v37
	v_mul_f32_e32 v37, v49, v49
	v_mul_f32_e32 v38, v51, v51
	v_fmac_f32_e32 v37, v48, v48
	v_fmac_f32_e32 v38, v50, v50
	v_add_f32_e32 v37, v37, v38
	v_add_f32_e32 v36, v36, v37
	v_add_f32_e32 v36, v52, v36
	ds_bpermute_b32 v37, v195, v36
	v_cvt_pk_bf16_f32 v46, v46, v47
	v_cvt_pk_bf16_f32 v47, v54, v55
	v_cvt_pk_bf16_f32 v38, v40, v41
	v_cvt_pk_bf16_f32 v39, v42, v43
	s_waitcnt lgkmcnt(0)
	v_add_f32_e32 v36, v36, v37
	ds_bpermute_b32 v37, v194, v36
	v_cvt_pk_bf16_f32 v40, v48, v49
	v_cvt_pk_bf16_f32 v41, v50, v51
	global_store_dwordx4 v[106:107], v[44:47], off
	global_store_dwordx4 v[106:107], v[38:41], off offset:256
	s_and_saveexec_b64 s[20:21], s[2:3]
	s_cbranch_execz .LBB0_1782
	s_waitcnt lgkmcnt(0)
	v_add_f32_e32 v38, v36, v37
	s_lshl_b32 s22, s39, 2
	v_lshlrev_b64 v[36:37], 6, v[104:105]
	s_ashr_i32 s23, s22, 31
	v_lshl_add_u64 v[36:37], s[10:11], 0, v[36:37]
	v_lshl_add_u64 v[36:37], s[22:23], 2, v[36:37]
	s_lshl_b32 s62, s45, 2
	v_lshl_add_u64 v[36:37], v[36:37], 0, s[62:63]
	global_store_dword v[36:37], v38, off
; DI u32x4 pack8(f32x4 a, f32x4 b) { u32x4 w; w.x = pk2(a[0], a[1]); w.y = pk2(a[2], a[3]); w.z = pk2(b[0], b[1]); w.w = pk2(b[2], b[3]); return w; }
;     DI void operator()(const pg8::Acc& acc, const pg8::Unit& u, int wr, int wc, int fr, int fq) const {
;     ...
;                 for (int m = 0; m < 4; ++m) { const int row = row0 + ai * 128 + m * 16; float ssq = 0.f;
; #pragma unroll
;                     for (int bj = 0; bj < 2; ++bj) { const u32x4 x = xv[m][bj];
;                         const f32x4 xa = (f32x4){bflo(x.x), bfhi(x.x), bflo(x.y), bfhi(x.y)} + acc[ai][bj][m][0] * scale, xb = (f32x4){bflo(x.z), bfhi(x.z), bflo(x.w), bfhi(x.w)} + acc[ai][bj][m][1] * scale;
;                         *(u32x4*)(XH + (size_t)row * DM + col0 + bj * 128) = pack8(xa, xb);
;                         ssq += ((xa[0] * xa[0] + xa[1] * xa[1]) + (xa[2] * xa[2] + xa[3] * xa[3])) + ((xb[0] * xb[0] + xb[1] * xb[1]) + (xb[2] * xb[2] + xb[3] * xb[3])); }
;                     ssq += __shfl_xor(ssq, 16); ssq += __shfl_xor(ssq, 32);
;                     if (fq == 0) SSP[(size_t)row * 16 + u.pn * 4 + wc] = ssq; }
.LBB0_1782:
	s_or_b64 exec, exec, s[20:21]
	v_lshlrev_b32_e32 v36, 16, v80
	s_waitcnt lgkmcnt(0)
	v_and_b32_e32 v37, 0xffff0000, v80
	v_lshlrev_b32_e32 v38, 16, v81
	v_and_b32_e32 v39, 0xffff0000, v81
	v_pk_add_f32 v[34:35], v[34:35], v[38:39]
	v_pk_add_f32 v[32:33], v[32:33], v[36:37]
	v_lshlrev_b32_e32 v36, 16, v82
	v_and_b32_e32 v37, 0xffff0000, v82
	v_lshlrev_b32_e32 v38, 16, v83
	v_and_b32_e32 v39, 0xffff0000, v83
	v_pk_add_f32 v[38:39], v[30:31], v[38:39]
	v_pk_add_f32 v[30:31], v[28:29], v[36:37]
	v_cvt_pk_bf16_f32 v28, v32, v33
	v_mul_f32_e32 v33, v33, v33
	v_fmac_f32_e32 v33, v32, v32
	v_mul_f32_e32 v32, v35, v35
	v_fmac_f32_e32 v32, v34, v34
	v_cvt_pk_bf16_f32 v29, v34, v35
	v_add_f32_e32 v32, v33, v32
	v_mul_f32_e32 v33, v31, v31
	v_mul_f32_e32 v34, v39, v39
	v_fmac_f32_e32 v33, v30, v30
	v_fmac_f32_e32 v34, v38, v38
	v_add_f32_e32 v33, v33, v34
	v_add_f32_e32 v36, v32, v33
	v_lshlrev_b32_e32 v32, 16, v76
	v_and_b32_e32 v33, 0xffff0000, v76
	v_lshlrev_b32_e32 v34, 16, v77
	v_and_b32_e32 v35, 0xffff0000, v77
	v_pk_add_f32 v[26:27], v[26:27], v[34:35]
	v_pk_add_f32 v[24:25], v[24:25], v[32:33]
	v_lshlrev_b32_e32 v32, 16, v78
	v_and_b32_e32 v33, 0xffff0000, v78
	v_lshlrev_b32_e32 v34, 16, v79
	v_and_b32_e32 v35, 0xffff0000, v79
	v_pk_add_f32 v[32:33], v[20:21], v[32:33]
	v_mul_f32_e32 v20, v25, v25
	v_mul_f32_e32 v21, v27, v27
	v_pk_add_f32 v[34:35], v[22:23], v[34:35]
	v_fmac_f32_e32 v20, v24, v24
	v_fmac_f32_e32 v21, v26, v26
	v_add_f32_e32 v20, v20, v21
	v_mul_f32_e32 v21, v33, v33
	v_mul_f32_e32 v22, v35, v35
	v_fmac_f32_e32 v21, v32, v32
	v_fmac_f32_e32 v22, v34, v34
	v_add_f32_e32 v21, v21, v22
	v_add_f32_e32 v20, v20, v21
	v_add_f32_e32 v20, v36, v20
	ds_bpermute_b32 v21, v195, v20
	v_cvt_pk_bf16_f32 v30, v30, v31
	v_cvt_pk_bf16_f32 v31, v38, v39
	v_cvt_pk_bf16_f32 v22, v24, v25
	v_cvt_pk_bf16_f32 v23, v26, v27
	s_waitcnt lgkmcnt(0)
	v_add_f32_e32 v20, v20, v21
	ds_bpermute_b32 v21, v194, v20
	v_cvt_pk_bf16_f32 v24, v32, v33
	v_cvt_pk_bf16_f32 v25, v34, v35
	global_store_dwordx4 v[102:103], v[28:31], off
	global_store_dwordx4 v[102:103], v[22:25], off offset:256
	s_and_saveexec_b64 s[20:21], s[2:3]
	s_cbranch_execz .LBB0_1784
	s_waitcnt lgkmcnt(0)
	v_add_f32_e32 v22, v20, v21
	s_lshl_b32 s22, s39, 2
	v_lshlrev_b64 v[20:21], 6, v[100:101]
	s_ashr_i32 s23, s22, 31
	v_lshl_add_u64 v[20:21], s[10:11], 0, v[20:21]
	v_lshl_add_u64 v[20:21], s[22:23], 2, v[20:21]
	s_lshl_b32 s62, s45, 2
	v_lshl_add_u64 v[20:21], v[20:21], 0, s[62:63]
	global_store_dword v[20:21], v22, off
.LBB0_1784:
	s_or_b64 exec, exec, s[20:21]
	v_lshlrev_b32_e32 v20, 16, v72
	s_waitcnt lgkmcnt(0)
	v_and_b32_e32 v21, 0xffff0000, v72
	v_lshlrev_b32_e32 v22, 16, v73
	v_and_b32_e32 v23, 0xffff0000, v73
	v_pk_add_f32 v[18:19], v[18:19], v[22:23]
	v_pk_add_f32 v[16:17], v[16:17], v[20:21]
	v_lshlrev_b32_e32 v20, 16, v74
	v_and_b32_e32 v21, 0xffff0000, v74
	v_lshlrev_b32_e32 v22, 16, v75
	v_and_b32_e32 v23, 0xffff0000, v75
	v_pk_add_f32 v[22:23], v[14:15], v[22:23]
	v_pk_add_f32 v[14:15], v[12:13], v[20:21]
	v_cvt_pk_bf16_f32 v12, v16, v17
	v_mul_f32_e32 v17, v17, v17
	v_fmac_f32_e32 v17, v16, v16
	v_mul_f32_e32 v16, v19, v19
	v_fmac_f32_e32 v16, v18, v18
	v_cvt_pk_bf16_f32 v13, v18, v19
	v_add_f32_e32 v16, v17, v16
	v_mul_f32_e32 v17, v15, v15
	v_mul_f32_e32 v18, v23, v23
	v_fmac_f32_e32 v17, v14, v14
	v_fmac_f32_e32 v18, v22, v22
	v_add_f32_e32 v17, v17, v18
	v_add_f32_e32 v20, v16, v17
	v_lshlrev_b32_e32 v16, 16, v68
	v_and_b32_e32 v17, 0xffff0000, v68
	v_lshlrev_b32_e32 v18, 16, v69
	v_and_b32_e32 v19, 0xffff0000, v69
	v_pk_add_f32 v[10:11], v[10:11], v[18:19]
	v_pk_add_f32 v[8:9], v[8:9], v[16:17]
	v_lshlrev_b32_e32 v16, 16, v70
	v_and_b32_e32 v17, 0xffff0000, v70
	v_lshlrev_b32_e32 v18, 16, v71
	v_and_b32_e32 v19, 0xffff0000, v71
	v_pk_add_f32 v[16:17], v[4:5], v[16:17]
	v_mul_f32_e32 v4, v9, v9
	v_mul_f32_e32 v5, v11, v11
	v_pk_add_f32 v[18:19], v[6:7], v[18:19]
	v_fmac_f32_e32 v4, v8, v8
	v_fmac_f32_e32 v5, v10, v10
	v_add_f32_e32 v4, v4, v5
	v_mul_f32_e32 v5, v17, v17
	v_mul_f32_e32 v6, v19, v19
	v_fmac_f32_e32 v5, v16, v16
	v_fmac_f32_e32 v6, v18, v18
	v_add_f32_e32 v5, v5, v6
	v_add_f32_e32 v4, v4, v5
	v_add_f32_e32 v4, v20, v4
	ds_bpermute_b32 v5, v195, v4
	v_cvt_pk_bf16_f32 v14, v14, v15
	v_cvt_pk_bf16_f32 v15, v22, v23
	v_cvt_pk_bf16_f32 v6, v8, v9
	v_cvt_pk_bf16_f32 v7, v10, v11
	s_waitcnt lgkmcnt(0)
	v_add_f32_e32 v4, v4, v5
	ds_bpermute_b32 v5, v194, v4
	v_cvt_pk_bf16_f32 v8, v16, v17
	v_cvt_pk_bf16_f32 v9, v18, v19
	global_store_dwordx4 v[98:99], v[12:15], off
	global_store_dwordx4 v[98:99], v[6:9], off offset:256
	s_and_saveexec_b64 s[20:21], s[2:3]
	s_cbranch_execz .LBB0_1786
	s_waitcnt lgkmcnt(0)
	v_add_f32_e32 v6, v4, v5
	s_lshl_b32 s22, s39, 2
	v_lshlrev_b64 v[4:5], 6, v[96:97]
	s_ashr_i32 s23, s22, 31
	v_lshl_add_u64 v[4:5], s[10:11], 0, v[4:5]
	v_lshl_add_u64 v[4:5], s[22:23], 2, v[4:5]
	s_lshl_b32 s62, s45, 2
	v_lshl_add_u64 v[4:5], v[4:5], 0, s[62:63]
	global_store_dword v[4:5], v6, off
